# epilogue de-serialisation: out-proj residual loads of a tile issued together (one latency) instead of 16 load-wait-store steps
# speedup vs baseline: 1.0063x; 1.0063x over previous
; __device__ void run_phase(const Params& p, int ph, char* smem) {
;     ...
;         EpiOutProj epi{l == 0 ? p.x : (const float*)p.out, p.out, p.xb, p.ssqE};
;         int tm, tn;
;         while (gemm_ticket(p.ctr + (l * 3 + 1) * 256, 8, tm, tn, smem)) gemm_tile64(p.mixed, p.WoutT + (size_t)l * 1024 * 1024, tm, tn, epi, smem, nullptr, 0);
.LBB0_63:
	s_or_b64 exec, exec, s[0:1]
	v_mov_b32_e32 v113, 0
	v_mov_b32_e32 v115, 1.0
	v_mov_b32_e32 v139, 0xff800000
	v_mov_b32_e32 v140, 0x41b17218
	s_mov_b64 s[0:1], 0

; template <class Epi>
; __device__ __forceinline__ void gemm_tile64(const bf16_t* A, const bf16_t* Bt, int tm, int tn, const Epi& epi, char* smem, const float* ssq, int nparts) {
;     ...
;             for (int m = 0; m < 4; ++m)
; #pragma unroll
;                 for (int n = 0; n < 4; ++n) acc[m][n] = __builtin_amdgcn_mfma_f32_16x16x32_bf16(bfr[n], af[m], acc[m][n], 0, 0, 0);
;     __device__ __forceinline__ void operator()(const f32x4 (&acc)[4][4], int tm, int tn, int wr, int wc, int fr, int fq, const float*) const {
;     ...
;         for (int m = 0; m < 4; ++m) {
;             const size_t row = (size_t)tm * 128 + wr * 64 + m * 16 + fr;
;             f32x4 o[4]; float sq = 0.f;
; #pragma unroll
;             for (int n = 0; n < 4; ++n) {
;                 o[n] = *(const f32x4*)(xin + row * 1024 + col0 + n * 4) + acc[m][n];
;                 *(f32x4*)(xout + row * 1024 + col0 + n * 4) = o[n];
.Lgo_nopf:
	s_waitcnt lgkmcnt(3)
	v_mfma_f32_16x16x32_bf16 v[60:63], v[80:83], v[88:91], v[60:63]
	v_mfma_f32_16x16x32_bf16 v[56:59], v[84:87], v[88:91], v[56:59]
	s_waitcnt lgkmcnt(1)
	v_mfma_f32_16x16x32_bf16 v[52:55], v[116:119], v[88:91], v[52:55]
	s_waitcnt lgkmcnt(0)
	v_mfma_f32_16x16x32_bf16 v[48:51], v[120:123], v[88:91], v[48:51]
	v_mfma_f32_16x16x32_bf16 v[44:47], v[80:83], v[92:95], v[44:47]
	v_mfma_f32_16x16x32_bf16 v[40:43], v[84:87], v[92:95], v[40:43]
	v_mfma_f32_16x16x32_bf16 v[36:39], v[116:119], v[92:95], v[36:39]
	v_mfma_f32_16x16x32_bf16 v[32:35], v[120:123], v[92:95], v[32:35]
	ds_read_b128 v[88:91], v108 offset:4096
	ds_read_b128 v[92:95], v108 offset:6144
	s_waitcnt lgkmcnt(1)
	v_mfma_f32_16x16x32_bf16 v[28:31], v[80:83], v[88:91], v[28:31]
	v_mfma_f32_16x16x32_bf16 v[24:27], v[84:87], v[88:91], v[24:27]
	v_mfma_f32_16x16x32_bf16 v[20:23], v[116:119], v[88:91], v[20:23]
	v_mfma_f32_16x16x32_bf16 v[16:19], v[120:123], v[88:91], v[16:19]
	s_waitcnt lgkmcnt(0)
	v_mfma_f32_16x16x32_bf16 v[4:7], v[80:83], v[92:95], v[4:7]
	v_mfma_f32_16x16x32_bf16 v[12:15], v[84:87], v[92:95], v[12:15]
	ds_read_b128 v[80:83], v111 offset:16384
	ds_read_b128 v[84:87], v111 offset:18432
	v_mfma_f32_16x16x32_bf16 v[8:11], v[116:119], v[92:95], v[8:11]
	v_mfma_f32_16x16x32_bf16 v[0:3], v[120:123], v[92:95], v[0:3]
	ds_read_b128 v[88:91], v110
	ds_read_b128 v[92:95], v110 offset:2048
	ds_read_b128 v[116:119], v111 offset:20480
	ds_read_b128 v[120:123], v111 offset:22528
	s_waitcnt lgkmcnt(3)
	v_mfma_f32_16x16x32_bf16 v[60:63], v[80:83], v[88:91], v[60:63]
	v_mfma_f32_16x16x32_bf16 v[56:59], v[84:87], v[88:91], v[56:59]
	s_waitcnt lgkmcnt(1)
	v_mfma_f32_16x16x32_bf16 v[52:55], v[116:119], v[88:91], v[52:55]
	s_waitcnt lgkmcnt(0)
	v_mfma_f32_16x16x32_bf16 v[48:51], v[120:123], v[88:91], v[48:51]
	ds_read_b128 v[88:91], v110 offset:4096
	ds_read_b128 v[144:147], v110 offset:6144
	v_mfma_f32_16x16x32_bf16 v[44:47], v[80:83], v[92:95], v[44:47]
	v_mfma_f32_16x16x32_bf16 v[40:43], v[84:87], v[92:95], v[40:43]
	v_mfma_f32_16x16x32_bf16 v[36:39], v[116:119], v[92:95], v[36:39]
	v_mfma_f32_16x16x32_bf16 v[32:35], v[120:123], v[92:95], v[32:35]
	s_waitcnt lgkmcnt(1)
	v_mfma_f32_16x16x32_bf16 v[28:31], v[80:83], v[88:91], v[28:31]
	v_mfma_f32_16x16x32_bf16 v[24:27], v[84:87], v[88:91], v[24:27]
	v_mfma_f32_16x16x32_bf16 v[20:23], v[116:119], v[88:91], v[20:23]
	v_mfma_f32_16x16x32_bf16 v[16:19], v[120:123], v[88:91], v[16:19]
	s_waitcnt lgkmcnt(0)
	v_mfma_f32_16x16x32_bf16 v[4:7], v[80:83], v[144:147], v[4:7]
	v_mfma_f32_16x16x32_bf16 v[12:15], v[84:87], v[144:147], v[12:15]
	v_mfma_f32_16x16x32_bf16 v[8:11], v[116:119], v[144:147], v[8:11]
	v_mfma_f32_16x16x32_bf16 v[0:3], v[120:123], v[144:147], v[0:3]
	s_cmp_eq_u32 s1, 17
	s_cbranch_scc0 .LBB0_71
	s_mov_b32 s21, 0
	s_movk_i32 s20, 0x780
	s_mov_b32 s13, 15
	v_lshlrev_b32_e32 v66, 6, v99
	s_lshl_b32 s20, s12, 7
	v_ashrrev_i32_e32 v67, 31, v66
	s_lshl_b32 s1, s0, 7
	v_lshlrev_b32_e32 v64, 6, v96
	v_lshlrev_b32_e32 v65, 4, v97
	v_lshl_add_u64 v[66:67], s[20:21], 0, v[66:67]
	v_or3_b32 v64, v64, s1, v65
	v_or_b32_e32 v66, v66, v98
	v_lshl_or_b32 v68, s0, 1, v96
	v_ashrrev_i32_e32 v65, 31, v64
	v_ashrrev_i32_e32 v69, 31, v68
	v_lshlrev_b64 v[76:77], 12, v[66:67]
	v_lshlrev_b64 v[70:71], 17, v[68:69]
	v_lshl_add_u64 v[72:73], s[22:23], 0, v[76:77]
	v_lshlrev_b64 v[68:69], 2, v[64:65]
	v_lshl_add_u64 v[78:79], v[72:73], 0, v[68:69]
	global_load_dwordx4 v[82:85], v[78:79], off
	global_load_dwordx4 v[86:89], v[78:79], off offset:16
	global_load_dwordx4 v[90:93], v[78:79], off offset:32
	global_load_dwordx4 v[116:119], v[78:79], off offset:48
	v_add_co_u32_e32 v94, vcc, 0x10000, v78
	s_nop 1
	v_addc_co_u32_e32 v95, vcc, 0, v79, vcc
	global_load_dwordx4 v[120:123], v[94:95], off
	global_load_dwordx4 v[144:147], v[94:95], off offset:16
	global_load_dwordx4 v[148:151], v[94:95], off offset:32
	global_load_dwordx4 v[152:155], v[94:95], off offset:48
	v_add_co_u32_e32 v94, vcc, 0x20000, v78
	s_nop 1
	v_addc_co_u32_e32 v95, vcc, 0, v79, vcc
	global_load_dwordx4 v[156:159], v[94:95], off
	global_load_dwordx4 v[160:163], v[94:95], off offset:16
	global_load_dwordx4 v[100:103], v[94:95], off offset:32
	global_load_dwordx4 v[104:107], v[94:95], off offset:48
	v_add_co_u32_e32 v94, vcc, 0x30000, v78
	s_nop 1
	v_addc_co_u32_e32 v95, vcc, 0, v79, vcc
	global_load_dwordx4 v[108:111], v[94:95], off
	global_load_dwordx4 v[136:139], v[94:95], off offset:16
	global_load_dwordx4 v[140:143], v[94:95], off offset:32
	global_load_dwordx4 v[112:115], v[94:95], off offset:48
	v_readlane_b32 s36, v165, 42
	v_readlane_b32 s46, v165, 52
	v_readlane_b32 s47, v165, 53
	v_cmp_lt_i32_e64 s[0:1], v134, v132
	v_readlane_b32 s50, v165, 56
	v_readlane_b32 s51, v165, 57
	v_cmp_eq_u32_e32 vcc, 0, v97
	v_readlane_b32 s37, v165, 43
	v_readlane_b32 s38, v165, 44
	v_readlane_b32 s39, v165, 45
	v_readlane_b32 s40, v165, 46
	v_readlane_b32 s41, v165, 47
	v_readlane_b32 s42, v165, 48
	v_readlane_b32 s43, v165, 49
	v_readlane_b32 s44, v165, 50
	v_readlane_b32 s45, v165, 51
	v_readlane_b32 s48, v165, 54
	v_readlane_b32 s49, v165, 55
	s_waitcnt vmcnt(0)
; __device__ __forceinline__ unsigned pk_bf16(float lo, float hi) { unsigned r; asm("v_cvt_pk_bf16_f32 %0, %1, %2" : "=v"(r) : "v"(lo), "v"(hi)); return r; }
;     __device__ __forceinline__ void operator()(const f32x4 (&acc)[4][4], int tm, int tn, int wr, int wc, int fr, int fq, const float*) const {
;     ...
;         for (int m = 0; m < 4; ++m) {
;             const size_t row = (size_t)tm * 128 + wr * 64 + m * 16 + fr;
;             f32x4 o[4]; float sq = 0.f;
; #pragma unroll
;             for (int n = 0; n < 4; ++n) {
;                 o[n] = *(const f32x4*)(xin + row * 1024 + col0 + n * 4) + acc[m][n];
;                 *(f32x4*)(xout + row * 1024 + col0 + n * 4) = o[n];
;                 sq += o[n][0] * o[n][0] + o[n][1] * o[n][1] + o[n][2] * o[n][2] + o[n][3] * o[n][3];
;             }
;             u32x4 w0, w1;
;             w0.x = pk_bf16(o[0][0], o[0][1]); w0.y = pk_bf16(o[0][2], o[0][3]); w0.z = pk_bf16(o[1][0], o[1][1]); w0.w = pk_bf16(o[1][2], o[1][3]);
;             w1.x = pk_bf16(o[2][0], o[2][1]); w1.y = pk_bf16(o[2][2], o[2][3]); w1.z = pk_bf16(o[3][0], o[3][1]); w1.w = pk_bf16(o[3][2], o[3][3]);
;             *(u32x4*)(xb + row * 1024 + col0) = w0; *(u32x4*)(xb + row * 1024 + col0 + 8) = w1;
;             sq += __shfl_xor(sq, 16); sq += __shfl_xor(sq, 32);
;             if (fq == 0) ssq[(size_t)(tn * 2 + wc) * T + row] = sq;
;         }
	v_pk_add_f32 v[60:61], v[60:61], v[82:83]
	v_lshl_add_u64 v[72:73], s[82:83], 0, v[76:77]
	v_pk_add_f32 v[62:63], v[62:63], v[84:85]
	v_lshl_add_u64 v[76:77], v[72:73], 0, v[68:69]
	global_store_dwordx4 v[76:77], v[60:63], off
	v_mul_f32_e32 v80, v61, v61
	v_fmac_f32_e32 v80, v60, v60
	v_fmac_f32_e32 v80, v62, v62
	v_fmac_f32_e32 v80, v63, v63
	v_cvt_pk_bf16_f32 v60, v60, v61
	v_cvt_pk_bf16_f32 v61, v62, v63
	v_pk_add_f32 v[56:57], v[56:57], v[86:87]
	s_nop 0
	v_mul_f32_e32 v72, v57, v57
	v_pk_add_f32 v[58:59], v[58:59], v[88:89]
	v_fmac_f32_e32 v72, v56, v56
	v_fmac_f32_e32 v72, v58, v58
	global_store_dwordx4 v[76:77], v[56:59], off offset:16
	v_fmac_f32_e32 v72, v59, v59
	v_add_f32_e32 v80, v80, v72
	v_cvt_pk_bf16_f32 v62, v56, v57
	v_cvt_pk_bf16_f32 v63, v58, v59
	v_pk_add_f32 v[52:53], v[52:53], v[90:91]
	s_nop 0
	v_mul_f32_e32 v72, v53, v53
	v_pk_add_f32 v[54:55], v[54:55], v[92:93]
	v_fmac_f32_e32 v72, v52, v52
	v_fmac_f32_e32 v72, v54, v54
	global_store_dwordx4 v[76:77], v[52:55], off offset:32
	v_fmac_f32_e32 v72, v55, v55
	v_add_f32_e32 v80, v80, v72
	v_cvt_pk_bf16_f32 v52, v52, v53
	v_cvt_pk_bf16_f32 v53, v54, v55
	v_pk_add_f32 v[48:49], v[48:49], v[116:117]
	v_pk_add_f32 v[50:51], v[50:51], v[118:119]
	v_mul_f32_e32 v72, v49, v49
	global_store_dwordx4 v[76:77], v[48:51], off offset:48
	v_fmac_f32_e32 v72, v48, v48
	v_cvt_pk_bf16_f32 v54, v48, v49
	v_fmac_f32_e32 v72, v50, v50
	v_lshlrev_b64 v[48:49], 11, v[66:67]
	v_lshl_add_u64 v[48:49], s[46:47], 0, v[48:49]
	v_lshl_add_u64 v[48:49], v[64:65], 1, v[48:49]
	v_fmac_f32_e32 v72, v51, v51
	v_cvt_pk_bf16_f32 v55, v50, v51
	global_store_dwordx4 v[48:49], v[60:63], off
	global_store_dwordx4 v[48:49], v[52:55], off offset:16
	v_cndmask_b32_e64 v48, v130, v134, s[0:1]
	v_add_f32_e32 v72, v80, v72
	v_lshlrev_b32_e32 v50, 2, v48
	ds_bpermute_b32 v48, v50, v72
	v_cmp_lt_i32_e64 s[0:1], v133, v132
	s_waitcnt lgkmcnt(0)
	v_add_f32_e32 v52, v72, v48
	v_cndmask_b32_e64 v48, v130, v133, s[0:1]
	v_lshlrev_b32_e32 v51, 2, v48
	ds_bpermute_b32 v53, v51, v52
	v_lshl_add_u64 v[48:49], s[50:51], 0, v[70:71]
	v_lshl_add_u64 v[48:49], v[66:67], 2, v[48:49]
	s_and_saveexec_b64 s[0:1], vcc
	s_cbranch_execz .LBB0_74
	s_waitcnt lgkmcnt(0)
	v_add_f32_e32 v52, v52, v53
	global_store_dword v[48:49], v52, off
.LBB0_74:
	s_or_b64 exec, exec, s[0:1]
	v_or_b32_e32 v60, 16, v66
	v_mov_b32_e32 v61, v67
	v_lshlrev_b64 v[56:57], 12, v[60:61]
	s_waitcnt lgkmcnt(0)
	v_lshl_add_u64 v[52:53], s[22:23], 0, v[56:57]
	v_lshl_add_u64 v[58:59], v[52:53], 0, v[68:69]
	v_lshl_add_u64 v[56:57], s[82:83], 0, v[56:57]
	v_lshl_add_u64 v[62:63], v[56:57], 0, v[68:69]
	v_readlane_b32 s36, v165, 42
	v_readlane_b32 s46, v165, 52
	v_readlane_b32 s47, v165, 53
	v_readlane_b32 s37, v165, 43
	v_readlane_b32 s38, v165, 44
	v_readlane_b32 s39, v165, 45
	v_readlane_b32 s40, v165, 46
	v_readlane_b32 s41, v165, 47
	v_readlane_b32 s42, v165, 48
	v_readlane_b32 s43, v165, 49
	v_readlane_b32 s44, v165, 50
	v_readlane_b32 s45, v165, 51
	v_readlane_b32 s48, v165, 54
	v_readlane_b32 s49, v165, 55
	v_readlane_b32 s50, v165, 56
	v_readlane_b32 s51, v165, 57
	v_pk_add_f32 v[46:47], v[46:47], v[122:123]
	v_pk_add_f32 v[44:45], v[44:45], v[120:121]
	global_store_dwordx4 v[62:63], v[44:47], off
	v_mul_f32_e32 v70, v45, v45
	v_cvt_pk_bf16_f32 v56, v44, v45
	v_fmac_f32_e32 v70, v44, v44
	v_fmac_f32_e32 v70, v46, v46
	v_fmac_f32_e32 v70, v47, v47
	v_cvt_pk_bf16_f32 v57, v46, v47
	v_pk_add_f32 v[42:43], v[42:43], v[146:147]
	v_pk_add_f32 v[40:41], v[40:41], v[144:145]
	global_store_dwordx4 v[62:63], v[40:43], off offset:16
	v_mul_f32_e32 v44, v41, v41
	v_fmac_f32_e32 v44, v40, v40
	v_fmac_f32_e32 v44, v42, v42
	v_fmac_f32_e32 v44, v43, v43
	v_pk_add_f32 v[38:39], v[38:39], v[150:151]
	v_pk_add_f32 v[36:37], v[36:37], v[148:149]
	global_store_dwordx4 v[62:63], v[36:39], off offset:32
	v_cvt_pk_bf16_f32 v58, v40, v41
	v_mul_f32_e32 v41, v37, v37
	v_fmac_f32_e32 v41, v36, v36
	v_fmac_f32_e32 v41, v38, v38
	v_add_f32_e32 v40, v70, v44
	v_fmac_f32_e32 v41, v39, v39
	v_add_f32_e32 v40, v40, v41
	v_cvt_pk_bf16_f32 v36, v36, v37
	v_cvt_pk_bf16_f32 v37, v38, v39
	v_cvt_pk_bf16_f32 v59, v42, v43
	v_pk_add_f32 v[32:33], v[32:33], v[152:153]
	s_nop 0
	v_mul_f32_e32 v41, v33, v33
	v_pk_add_f32 v[34:35], v[34:35], v[154:155]
	v_fmac_f32_e32 v41, v32, v32
	v_fmac_f32_e32 v41, v34, v34
	v_fmac_f32_e32 v41, v35, v35
	v_add_f32_e32 v40, v40, v41
	ds_bpermute_b32 v41, v50, v40
	global_store_dwordx4 v[62:63], v[32:35], off offset:48
	v_cvt_pk_bf16_f32 v38, v32, v33
	v_cvt_pk_bf16_f32 v39, v34, v35
	s_waitcnt lgkmcnt(0)
	s_nop 0
	v_add_f32_e32 v32, v40, v41
	ds_bpermute_b32 v33, v51, v32
	v_lshlrev_b64 v[34:35], 11, v[60:61]
	v_lshl_add_u64 v[34:35], s[46:47], 0, v[34:35]
	v_lshl_add_u64 v[34:35], v[64:65], 1, v[34:35]
	global_store_dwordx4 v[34:35], v[56:59], off
	global_store_dwordx4 v[34:35], v[36:39], off offset:16
	s_and_saveexec_b64 s[0:1], vcc
	s_cbranch_execz .LBB0_76
	s_waitcnt lgkmcnt(0)
	v_add_f32_e32 v32, v32, v33
	global_store_dword v[48:49], v32, off offset:64
; __device__ __forceinline__ unsigned pk_bf16(float lo, float hi) { unsigned r; asm("v_cvt_pk_bf16_f32 %0, %1, %2" : "=v"(r) : "v"(lo), "v"(hi)); return r; }
;     __device__ __forceinline__ void operator()(const f32x4 (&acc)[4][4], int tm, int tn, int wr, int wc, int fr, int fq, const float*) const {
;     ...
;         for (int m = 0; m < 4; ++m) {
;             const size_t row = (size_t)tm * 128 + wr * 64 + m * 16 + fr;
;             f32x4 o[4]; float sq = 0.f;
; #pragma unroll
;             for (int n = 0; n < 4; ++n) {
;                 o[n] = *(const f32x4*)(xin + row * 1024 + col0 + n * 4) + acc[m][n];
;                 *(f32x4*)(xout + row * 1024 + col0 + n * 4) = o[n];
;                 sq += o[n][0] * o[n][0] + o[n][1] * o[n][1] + o[n][2] * o[n][2] + o[n][3] * o[n][3];
;             }
;             u32x4 w0, w1;
;             w0.x = pk_bf16(o[0][0], o[0][1]); w0.y = pk_bf16(o[0][2], o[0][3]); w0.z = pk_bf16(o[1][0], o[1][1]); w0.w = pk_bf16(o[1][2], o[1][3]);
;             w1.x = pk_bf16(o[2][0], o[2][1]); w1.y = pk_bf16(o[2][2], o[2][3]); w1.z = pk_bf16(o[3][0], o[3][1]); w1.w = pk_bf16(o[3][2], o[3][3]);
;             *(u32x4*)(xb + row * 1024 + col0) = w0; *(u32x4*)(xb + row * 1024 + col0 + 8) = w1;
;             sq += __shfl_xor(sq, 16); sq += __shfl_xor(sq, 32);
;             if (fq == 0) ssq[(size_t)(tn * 2 + wc) * T + row] = sq;
;         }
.LBB0_76:
	s_or_b64 exec, exec, s[0:1]
	v_or_b32_e32 v40, 32, v66
	v_mov_b32_e32 v41, v67
	v_lshlrev_b64 v[36:37], 12, v[40:41]
	s_waitcnt lgkmcnt(0)
	v_lshl_add_u64 v[32:33], s[22:23], 0, v[36:37]
	v_lshl_add_u64 v[38:39], v[32:33], 0, v[68:69]
	v_lshl_add_u64 v[36:37], s[82:83], 0, v[36:37]
	v_lshl_add_u64 v[42:43], v[36:37], 0, v[68:69]
	v_readlane_b32 s36, v165, 42
	v_readlane_b32 s46, v165, 52
	v_readlane_b32 s47, v165, 53
	v_readlane_b32 s37, v165, 43
	v_readlane_b32 s38, v165, 44
	v_readlane_b32 s39, v165, 45
	v_readlane_b32 s40, v165, 46
	v_readlane_b32 s41, v165, 47
	v_readlane_b32 s42, v165, 48
	v_readlane_b32 s43, v165, 49
	v_readlane_b32 s44, v165, 50
	v_readlane_b32 s45, v165, 51
	v_readlane_b32 s48, v165, 54
	v_readlane_b32 s49, v165, 55
	v_readlane_b32 s50, v165, 56
	v_readlane_b32 s51, v165, 57
	v_pk_add_f32 v[30:31], v[30:31], v[158:159]
	v_pk_add_f32 v[28:29], v[28:29], v[156:157]
	global_store_dwordx4 v[42:43], v[28:31], off
	v_mul_f32_e32 v44, v29, v29
	v_cvt_pk_bf16_f32 v36, v28, v29
	v_fmac_f32_e32 v44, v28, v28
	v_fmac_f32_e32 v44, v30, v30
	v_fmac_f32_e32 v44, v31, v31
	v_cvt_pk_bf16_f32 v37, v30, v31
	v_pk_add_f32 v[26:27], v[26:27], v[162:163]
	v_pk_add_f32 v[24:25], v[24:25], v[160:161]
	global_store_dwordx4 v[42:43], v[24:27], off offset:16
	v_mul_f32_e32 v28, v25, v25
	v_fmac_f32_e32 v28, v24, v24
	v_fmac_f32_e32 v28, v26, v26
	v_fmac_f32_e32 v28, v27, v27
	v_pk_add_f32 v[22:23], v[22:23], v[102:103]
	v_pk_add_f32 v[20:21], v[20:21], v[100:101]
	global_store_dwordx4 v[42:43], v[20:23], off offset:32
	v_cvt_pk_bf16_f32 v38, v24, v25
	v_mul_f32_e32 v25, v21, v21
	v_fmac_f32_e32 v25, v20, v20
	v_fmac_f32_e32 v25, v22, v22
	v_add_f32_e32 v24, v44, v28
	v_fmac_f32_e32 v25, v23, v23
	v_add_f32_e32 v24, v24, v25
	v_cvt_pk_bf16_f32 v20, v20, v21
	v_cvt_pk_bf16_f32 v21, v22, v23
	v_cvt_pk_bf16_f32 v39, v26, v27
	v_pk_add_f32 v[16:17], v[16:17], v[104:105]
	s_nop 0
	v_mul_f32_e32 v25, v17, v17
	v_pk_add_f32 v[18:19], v[18:19], v[106:107]
	v_fmac_f32_e32 v25, v16, v16
	v_fmac_f32_e32 v25, v18, v18
	v_fmac_f32_e32 v25, v19, v19
	v_add_f32_e32 v24, v24, v25
	ds_bpermute_b32 v25, v50, v24
	global_store_dwordx4 v[42:43], v[16:19], off offset:48
	v_cvt_pk_bf16_f32 v22, v16, v17
	v_cvt_pk_bf16_f32 v23, v18, v19
	s_waitcnt lgkmcnt(0)
	s_nop 0
	v_add_f32_e32 v16, v24, v25
	ds_bpermute_b32 v17, v51, v16
	v_lshlrev_b64 v[18:19], 11, v[40:41]
	v_lshl_add_u64 v[18:19], s[46:47], 0, v[18:19]
	v_lshl_add_u64 v[18:19], v[64:65], 1, v[18:19]
	global_store_dwordx4 v[18:19], v[36:39], off
	global_store_dwordx4 v[18:19], v[20:23], off offset:16
	s_and_saveexec_b64 s[0:1], vcc
	s_cbranch_execz .LBB0_78
	s_waitcnt lgkmcnt(0)
	v_add_f32_e32 v16, v16, v17
	global_store_dword v[48:49], v16, off offset:128
.LBB0_78:
	s_or_b64 exec, exec, s[0:1]
	v_or_b32_e32 v66, 48, v66
	v_lshlrev_b64 v[20:21], 12, v[66:67]
	s_waitcnt lgkmcnt(0)
	v_lshl_add_u64 v[16:17], s[22:23], 0, v[20:21]
	v_lshl_add_u64 v[22:23], v[16:17], 0, v[68:69]
	v_lshl_add_u64 v[20:21], s[82:83], 0, v[20:21]
	v_lshl_add_u64 v[24:25], v[20:21], 0, v[68:69]
	v_readlane_b32 s36, v165, 42
	v_readlane_b32 s46, v165, 52
	v_readlane_b32 s47, v165, 53
	v_readlane_b32 s37, v165, 43
	v_readlane_b32 s38, v165, 44
	v_readlane_b32 s39, v165, 45
	v_readlane_b32 s40, v165, 46
	v_readlane_b32 s41, v165, 47
	v_readlane_b32 s42, v165, 48
	v_readlane_b32 s43, v165, 49
	v_readlane_b32 s44, v165, 50
	v_readlane_b32 s45, v165, 51
	v_readlane_b32 s48, v165, 54
	v_readlane_b32 s49, v165, 55
	v_readlane_b32 s50, v165, 56
	v_readlane_b32 s51, v165, 57
	v_pk_add_f32 v[6:7], v[6:7], v[110:111]
	v_pk_add_f32 v[4:5], v[4:5], v[108:109]
	global_store_dwordx4 v[24:25], v[4:7], off
	v_mul_f32_e32 v26, v5, v5
	v_cvt_pk_bf16_f32 v20, v4, v5
	v_fmac_f32_e32 v26, v4, v4
	v_fmac_f32_e32 v26, v6, v6
	v_fmac_f32_e32 v26, v7, v7
	v_cvt_pk_bf16_f32 v21, v6, v7
	v_pk_add_f32 v[14:15], v[14:15], v[138:139]
	v_pk_add_f32 v[12:13], v[12:13], v[136:137]
	global_store_dwordx4 v[24:25], v[12:15], off offset:16
	v_mul_f32_e32 v4, v13, v13
	v_fmac_f32_e32 v4, v12, v12
	v_fmac_f32_e32 v4, v14, v14
	v_fmac_f32_e32 v4, v15, v15
	v_add_f32_e32 v4, v26, v4
	v_pk_add_f32 v[10:11], v[10:11], v[142:143]
	v_pk_add_f32 v[8:9], v[8:9], v[140:141]
	global_store_dwordx4 v[24:25], v[8:11], off offset:32
	v_mul_f32_e32 v5, v9, v9
	v_fmac_f32_e32 v5, v8, v8
	v_fmac_f32_e32 v5, v10, v10
	v_fmac_f32_e32 v5, v11, v11
	v_add_f32_e32 v4, v4, v5
	v_cvt_pk_bf16_f32 v22, v12, v13
	v_cvt_pk_bf16_f32 v23, v14, v15
	v_pk_add_f32 v[0:1], v[0:1], v[112:113]
	s_nop 0
	v_mul_f32_e32 v5, v1, v1
	v_pk_add_f32 v[2:3], v[2:3], v[114:115]
	v_fmac_f32_e32 v5, v0, v0
	v_fmac_f32_e32 v5, v2, v2
	v_fmac_f32_e32 v5, v3, v3
	v_add_f32_e32 v12, v4, v5
	v_cvt_pk_bf16_f32 v4, v8, v9
	ds_bpermute_b32 v8, v50, v12
	global_store_dwordx4 v[24:25], v[0:3], off offset:48
	v_cvt_pk_bf16_f32 v6, v0, v1
	v_cvt_pk_bf16_f32 v7, v2, v3
	v_cvt_pk_bf16_f32 v5, v10, v11
	s_waitcnt lgkmcnt(0)
	s_nop 0
	v_add_f32_e32 v0, v12, v8
	ds_bpermute_b32 v1, v51, v0
	v_lshlrev_b64 v[2:3], 11, v[66:67]
	v_lshl_add_u64 v[2:3], s[46:47], 0, v[2:3]
	v_lshl_add_u64 v[2:3], v[64:65], 1, v[2:3]
	global_store_dwordx4 v[2:3], v[20:23], off
	global_store_dwordx4 v[2:3], v[4:7], off offset:16
	s_and_saveexec_b64 s[0:1], vcc
	s_xor_b64 s[0:1], exec, s[0:1]
	s_cbranch_execz .LBB0_63
	s_waitcnt lgkmcnt(0)
	v_add_f32_e32 v0, v0, v1
	global_store_dword v[48:49], v0, off offset:192
	s_branch .LBB0_63
